# protocol-wave latency trimming: L1 invalidate issued after the arrival atomic returns (overlaps the leader's L2 writeback), no ack waits after generation atomics; on top of v82
# speedup vs baseline: 1.0098x; 1.0098x over previous
; __device__ __forceinline__ unsigned xb_ld(unsigned* p)              { return __hip_atomic_load(p, __ATOMIC_RELAXED, __HIP_MEMORY_SCOPE_AGENT); }
; __device__ __forceinline__ unsigned xb_add(unsigned* p, unsigned v) { return __hip_atomic_fetch_add(p, v, __ATOMIC_RELAXED, __HIP_MEMORY_SCOPE_AGENT); }
; #define XB_SPIN(cond, bar) do { unsigned _sp = 0; while (cond) { __builtin_amdgcn_s_sleep(1); \
;     if ((++_sp & 255u) == 0u) { if (xb_ld(&(bar)[XB_TMO])) break; if (_sp > XB_SPIN_CAP) { atomicAdd(&(bar)[XB_TMO], 1u); break; } } } } while (0)
; __device__ __forceinline__ void xcd_barrier(const XcdBarrier& b) {
;     ...
;         unsigned nloc = b.st[0], nx = b.st[1];
;         if (nloc == 0u) { xcd_barrier_complete(bar, b.x, nloc, nx); b.st[0] = nloc; b.st[1] = nx; }
;         const unsigned old = xb_add(&bar[XB_XSUB(b.x)], 1u);
;         const unsigned gen = old / nloc;
;         if (old + 1u == (gen + 1u) * nloc) {
;             __builtin_amdgcn_fence(__ATOMIC_RELEASE, "agent");
;             asm volatile("s_waitcnt vmcnt(0)" ::: "memory");
;             const unsigned og = xb_add(&bar[XB_TOP], 1u);
;             const unsigned tg = og / nx;
;             if (og + 1u == (tg + 1u) * nx) xb_add(&bar[XB_TOPGEN], 1u);
;             else XB_SPIN(xb_ld(&bar[XB_TOPGEN]) == tg, bar);
;             __builtin_amdgcn_fence(__ATOMIC_ACQUIRE, "agent");
;             xb_add(&bar[XB_XGEN(b.x)], 1u);
;             asm volatile("s_waitcnt vmcnt(0)" ::: "memory");
;         } else {
;             XB_SPIN(xb_ld(&bar[XB_XGEN(b.x)]) == gen, bar);
.LBB0_67:
	s_or_b64 exec, exec, s[8:9]
	v_cvt_f32_u32_e32 v4, v2
	s_waitcnt vmcnt(0)
	buffer_inv sc1
	v_readfirstlane_b32 s6, v3
	v_sub_u32_e32 v3, 0, v2
	v_rcp_iflag_f32_e32 v4, v4
	v_add_u32_e32 v5, s6, v1
	v_mul_f32_e32 v4, 0x4f7ffffe, v4
	v_cvt_u32_f32_e32 v4, v4
	v_mul_lo_u32 v1, v3, v4
	v_mul_hi_u32 v1, v4, v1
	v_add_u32_e32 v1, v4, v1
	v_mul_hi_u32 v1, v5, v1
	v_mul_lo_u32 v3, v1, v2
	v_sub_u32_e32 v3, v5, v3
	v_add_u32_e32 v4, 1, v1
	v_cmp_ge_u32_e32 vcc, v3, v2
	s_nop 1
	v_cndmask_b32_e32 v1, v1, v4, vcc
	v_sub_u32_e32 v4, v3, v2
	v_cndmask_b32_e32 v3, v3, v4, vcc
	v_add_u32_e32 v4, 1, v1
	v_cmp_ge_u32_e32 vcc, v3, v2
	v_add_u32_e32 v3, 1, v5
	s_nop 0
	v_cndmask_b32_e32 v1, v1, v4, vcc
	v_mul_lo_u32 v4, v2, v1
	v_add_u32_e32 v2, v4, v2
	v_cmp_ne_u32_e32 vcc, v3, v2
	s_and_saveexec_b64 s[6:7], vcc
	s_xor_b64 s[6:7], exec, s[6:7]
	s_cbranch_execz .LBB0_81
	s_waitcnt lgkmcnt(0)
	v_mov_b32_e32 v0, 0x2000
	global_load_dword v0, v0, s[4:5] offset:1024 sc1
	s_add_u32 s12, s4, 0x2400
	s_addc_u32 s13, s5, 0
	s_waitcnt vmcnt(0)
	v_cmp_eq_u32_e32 vcc, v0, v1
	s_and_saveexec_b64 s[8:9], vcc
	s_cbranch_execz .LBB0_80
	s_add_u32 s10, s28, 0x1e700200
	s_addc_u32 s11, s29, 0
	s_mov_b32 s16, 1
	s_mov_b64 s[14:15], 0
	v_mov_b32_e32 v0, 0
	s_branch .LBB0_71

; __device__ __forceinline__ unsigned xb_ld(unsigned* p)              { return __hip_atomic_load(p, __ATOMIC_RELAXED, __HIP_MEMORY_SCOPE_AGENT); }
; __device__ __forceinline__ unsigned xb_add(unsigned* p, unsigned v) { return __hip_atomic_fetch_add(p, v, __ATOMIC_RELAXED, __HIP_MEMORY_SCOPE_AGENT); }
; #define XB_SPIN(cond, bar) do { unsigned _sp = 0; while (cond) { __builtin_amdgcn_s_sleep(1); \
;     if ((++_sp & 255u) == 0u) { if (xb_ld(&(bar)[XB_TMO])) break; if (_sp > XB_SPIN_CAP) { atomicAdd(&(bar)[XB_TMO], 1u); break; } } } } while (0)
; __device__ __forceinline__ void xcd_barrier(const XcdBarrier& b) {
;     ...
;         unsigned nloc = b.st[0], nx = b.st[1];
;         if (nloc == 0u) { xcd_barrier_complete(bar, b.x, nloc, nx); b.st[0] = nloc; b.st[1] = nx; }
;         const unsigned old = xb_add(&bar[XB_XSUB(b.x)], 1u);
;         const unsigned gen = old / nloc;
;         if (old + 1u == (gen + 1u) * nloc) {
;             __builtin_amdgcn_fence(__ATOMIC_RELEASE, "agent");
;             asm volatile("s_waitcnt vmcnt(0)" ::: "memory");
;             const unsigned og = xb_add(&bar[XB_TOP], 1u);
;             const unsigned tg = og / nx;
;             if (og + 1u == (tg + 1u) * nx) xb_add(&bar[XB_TOPGEN], 1u);
;             else XB_SPIN(xb_ld(&bar[XB_TOPGEN]) == tg, bar);
;             __builtin_amdgcn_fence(__ATOMIC_ACQUIRE, "agent");
;             xb_add(&bar[XB_XGEN(b.x)], 1u);
;             asm volatile("s_waitcnt vmcnt(0)" ::: "memory");
;         } else {
;             XB_SPIN(xb_ld(&bar[XB_XGEN(b.x)]) == gen, bar);
.LBB0_1278:
	s_or_b64 exec, exec, s[8:9]
	v_cvt_f32_u32_e32 v4, v2
	s_waitcnt vmcnt(0)
	buffer_inv sc1
	v_readfirstlane_b32 s3, v3
	v_sub_u32_e32 v3, 0, v2
	v_rcp_iflag_f32_e32 v4, v4
	v_add_u32_e32 v5, s3, v1
	v_mul_f32_e32 v4, 0x4f7ffffe, v4
	v_cvt_u32_f32_e32 v4, v4
	v_mul_lo_u32 v1, v3, v4
	v_mul_hi_u32 v1, v4, v1
	v_add_u32_e32 v1, v4, v1
	v_mul_hi_u32 v1, v5, v1
	v_mul_lo_u32 v3, v1, v2
	v_sub_u32_e32 v3, v5, v3
	v_add_u32_e32 v4, 1, v1
	v_cmp_ge_u32_e32 vcc, v3, v2
	s_nop 1
	v_cndmask_b32_e32 v1, v1, v4, vcc
	v_sub_u32_e32 v4, v3, v2
	v_cndmask_b32_e32 v3, v3, v4, vcc
	v_add_u32_e32 v4, 1, v1
	v_cmp_ge_u32_e32 vcc, v3, v2
	v_add_u32_e32 v3, 1, v5
	s_nop 0
	v_cndmask_b32_e32 v1, v1, v4, vcc
	v_mul_lo_u32 v4, v2, v1
	v_add_u32_e32 v2, v4, v2
	v_cmp_ne_u32_e32 vcc, v3, v2
	s_and_saveexec_b64 s[6:7], vcc
	s_xor_b64 s[6:7], exec, s[6:7]
	s_cbranch_execz .LBB0_1292
	s_waitcnt lgkmcnt(0)
	v_mov_b32_e32 v0, 0x2000
	global_load_dword v0, v0, s[4:5] offset:1024 sc1
	s_add_u32 s12, s4, 0x2400
	s_addc_u32 s13, s5, 0
	s_waitcnt vmcnt(0)
	v_cmp_eq_u32_e32 vcc, v0, v1
	s_and_saveexec_b64 s[8:9], vcc
	s_cbranch_execz .LBB0_1291
	s_add_u32 s10, s28, 0x1e700200
	s_addc_u32 s11, s29, 0
	s_mov_b32 s3, 1
	s_mov_b64 s[14:15], 0
	v_mov_b32_e32 v0, 0
	s_branch .LBB0_1282
